# dilated attention inner loop hand-rewritten: two-pass softmax over 5 subtiles in registers, loads overlap compute
# speedup vs baseline: 1.0085x; 1.0085x over previous
; #define LAS __attribute__((address_space(3)))
; __global__ void __launch_bounds__(NTHR, 2) fwd_mega(Args args) {
;     ...
;                 for (int e = tid; e < 36 * 192; e += NTHR) { const int tb_ = e / 192, st_ = e - 192 * tb_ - 32, p_ = tb_ / 12, h_ = tb_ - 12 * p_, r_ = (p_ == 0) ? 1 : (p_ == 1 ? 4 : 16); float tv = -INFINITY;
;                     if (st_ >= 0 && st_ <= 128) { const int dist = st_ * r_; int bk;
;                         if (dist < 16) bk = dist; else { bk = 16 + (int)(logf((float)dist * (1.f / 16.f)) / logf(128.f) * 16.f); bk = bk > 31 ? 31 : bk; }
;                         tv = ap->in[I_REL][bk * 12 + h_] * LOG2E; }
;                     ((LAS float*)(lds + DIL_TBLS))[e] = tv; }
;                 if (vcu < 4608) { DIL_MAKE(cur, vcu); DIL_GLOAD(cur, RG); }
;                 for (int u = vcu; u < 4608; u += G) {
.LBB0_520:
	s_or_b64 exec, exec, s[26:27]
	s_ashr_i32 s17, s16, 31
	s_and_b64 s[26:27], s[12:13], exec
	s_cselect_b32 s6, 10, 12
	s_and_b64 s[26:27], s[10:11], exec
	s_cselect_b32 s6, 8, s6
	s_lshl_b64 s[16:17], s[16:17], s6
	s_add_u32 s6, s16, s22
	s_addc_u32 s9, s17, s23
	s_mul_i32 s16, s9, 0x1200
	s_mul_hi_u32 s17, s6, 0x1200
	s_add_i32 s17, s17, s16
	s_mul_i32 s16, s6, 0x1200
	s_add_u32 s21, s1, s16
	s_addc_u32 s22, s2, s17
	s_mul_i32 s17, s5, 0x3000000
	s_mul_hi_i32 s16, s5, 0x3000000
	s_add_u32 s17, s72, s17
	s_mul_i32 s23, s9, 0x600
	s_mul_hi_u32 s26, s6, 0x600
	s_addc_u32 s16, s73, s16
	s_add_i32 s26, s26, s23
	s_mul_i32 s23, s6, 0x600
	s_add_u32 s23, s17, s23
	s_addc_u32 s26, s16, s26
	s_and_b64 s[16:17], s[12:13], exec
	s_movk_i32 s16, 0x3000
	s_mul_hi_i32 s17, s5, 0x180000
	s_mul_i32 s5, s5, 0x180000
	v_readlane_b32 s36, v255, 3
	s_cselect_b32 s16, 0xc00, s16
	v_readlane_b32 s37, v255, 4
	s_add_u32 s5, s36, s5
	s_mul_i32 s9, s9, 48
	s_mul_hi_u32 s27, s6, 48
	s_addc_u32 s17, s37, s17
	s_add_i32 s27, s27, s9
	s_mul_i32 s6, s6, 48
	s_add_u32 s30, s5, s6
	s_addc_u32 s17, s17, s27
	s_ashr_i32 s9, s8, 31
	s_and_b64 s[12:13], s[12:13], exec
	s_cselect_b32 s5, 48, 0xc0
	s_and_b64 s[10:11], s[10:11], exec
	v_ashrrev_i32_e32 v2, 1, v247
	s_movk_i32 s12, 0xffe0
	s_cselect_b32 s5, 12, s5
	s_cselect_b32 s6, 0x300, s16
	s_add_u32 s10, s21, s14
	v_bfi_b32 v142, s12, v2, v247
	v_lshrrev_b32_e32 v5, 2, v247
	s_addc_u32 s11, s22, s15
	v_mad_i64_i32 v[2:3], s[12:13], s7, v142, 0
	v_and_b32_e32 v4, 8, v5
	v_lshl_add_u64 v[2:3], v[2:3], 1, s[10:11]
	v_lshlrev_b32_e32 v6, 1, v4
	v_mov_b32_e32 v7, v1
	v_lshl_add_u64 v[2:3], v[2:3], 0, v[6:7]
	global_load_dwordx4 v[110:113], v[2:3], off offset:96
	global_load_dwordx4 v[106:109], v[2:3], off offset:64
	global_load_dwordx4 v[102:105], v[2:3], off offset:32
	global_load_dwordx4 v[98:101], v[2:3], off
	v_lshlrev_b32_e32 v2, 4, v247
	v_and_b32_e32 v2, 0x70, v2
	v_add_u32_e32 v3, 0, v2
	v_lshrrev_b32_e32 v2, 1, v247
	s_lshl_b64 s[8:9], s[8:9], 2
	v_and_b32_e32 v6, 16, v2
	v_lshrrev_b32_e32 v2, 3, v247
	v_xor_b32_e32 v9, 32, v235
	v_add_u32_e32 v10, 64, v236
	s_add_u32 s8, s30, s8
	v_and_b32_e32 v2, 4, v2
	v_cmp_lt_i32_e32 vcc, v9, v10
	v_and_b32_e32 v131, 31, v247
	s_addc_u32 s9, s17, s9
	v_and_or_b32 v5, v5, 3, v2
	v_lshlrev_b32_e32 v7, 1, v247
	v_lshlrev_b32_e32 v8, 3, v226
	v_cndmask_b32_e32 v9, v235, v9, vcc
	s_add_u32 s12, s23, s14
	v_mul_u32_u24_e32 v5, 0x90, v5
	v_and_b32_e32 v7, 32, v7
	v_and_b32_e32 v8, 24, v8
	v_lshlrev_b32_e32 v133, 2, v9
	v_mul_lo_u32 v9, v130, s87
	v_mul_lo_u32 v10, v132, s87
	v_mul_lo_u32 v11, v134, s87
	v_mul_lo_u32 v12, v136, s87
	v_mul_lo_u32 v13, v138, s87
	v_mul_lo_u32 v14, v140, s87
	v_lshlrev_b32_e32 v15, 2, v131
	s_addc_u32 s13, s26, s15
	s_mov_b32 s26, 0
	v_cmp_gt_u32_e64 s[40:41], 32, v226
	v_sub_u32_e32 v135, v15, v6
	v_mad_u32_u24 v137, v131, s87, v6
	v_add3_u32 v139, v5, v7, v8
	s_mov_b64 s[16:17], 0
	v_add_u32_e32 v141, v3, v9
	v_add_u32_e32 v143, v3, v10
	v_add_u32_e32 v148, v3, v11
	v_add_u32_e32 v149, v3, v12
	v_add_u32_e32 v150, v3, v13
	v_add_u32_e32 v151, v3, v14
	v_lshlrev_b32_e32 v144, 1, v4
	v_lshlrev_b32_e32 v146, 1, v2
	s_mov_b64 s[22:23], 0
	s_mov_b32 s27, 0
	s_mov_b32 s21, 0
	s_waitcnt vmcnt(0)
	s_branch .LBB0_522

; #define LAS __attribute__((address_space(3)))
; #define MFMA32(a, b, c) __builtin_amdgcn_mfma_f32_32x32x16_bf16((a), (b), (c), 0, 0, 0)
; DI void dil_compute(LAS char* lds, const DilU& u, const LAS float* tbl, int tid, const bf16x8 (&qf)[4]) {
;     ...
;     for (int a = 0; a < 5; ++a) {
;         const int s = w + a;
;         if (32 * s < u.row_lo) continue;
;         const LAS char* Kt = lds + DIL_KB + 32 * s * DIL_PITCH; const LAS char* Vt = lds + DIL_VB + 32 * s * DIL_PITCH;
;         f32x16 p;
; #pragma unroll
;         for (int r = 0; r < 16; ++r) p[r] = 0.f;
; #pragma unroll
;         for (int d0 = 0; d0 < 4; ++d0) { const bf16x8 kf = frag_row(Kt, DIL_PITCH, 0, 16 * d0, lane); p = MFMA32(kf, qf[d0], p); }
;         { const LAS float* tb = tbl + (32 + 128 + r32 - 32 * a - 4 * hi);
; #pragma unroll
;           for (int r = 0; r < 16; ++r) p[r] += tb[-((r & 3) + 8 * (r >> 2))]; }
;         float mx = p[0];
; #pragma unroll
;         for (int r = 1; r < 16; ++r) mx = fmaxf(mx, p[r]);
.LBB0_537:
	s_mul_hi_i32 s10, s20, 0x2aaaaaab
	s_lshr_b32 s11, s10, 31
	s_ashr_i32 s10, s10, 8
	s_add_i32 s10, s10, s11
	s_mul_i32 s11, s10, 0x600
	s_sub_i32 s11, s20, s11
	s_mul_i32 s20, s11, 0x2aab
	s_lshr_b32 s30, s20, 31
	s_lshr_b32 s20, s20, 17
	s_add_i32 s20, s20, s30
	s_mul_i32 s20, s20, 12
	s_sub_i32 s11, s11, s20
	s_sext_i32_i16 s11, s11
	v_readfirstlane_b32 s20, v247
	s_ashr_i32 s20, s20, 6
	s_mulk_i32 s10, 0x2400
	s_mulk_i32 s11, 0x300
	s_add_i32 s11, s11, s10
	s_lshl_b32 s10, s20, 5
	s_mulk_i32 s20, 0x1200
	v_add_u32_e32 v147, s11, v135
	v_add_u32_e32 v152, s20, v137
	v_add_u32_e32 v153, s20, v139
	ds_read_b128 v[2:5], v152 offset:0
	ds_read_b128 v[6:9], v152 offset:32
	ds_read_b128 v[10:13], v152 offset:64
	ds_read_b128 v[14:17], v152 offset:96
	v_add_u32_e32 v222, 0x1b214, v147
	ds_read2_b32 v[18:19], v222 offset0:27 offset1:26
	ds_read2_b32 v[20:21], v222 offset0:25 offset1:24
	ds_read2_b32 v[22:23], v222 offset0:19 offset1:18
	ds_read2_b32 v[24:25], v222 offset0:17 offset1:16
	ds_read2_b32 v[26:27], v222 offset0:11 offset1:10
	ds_read2_b32 v[28:29], v222 offset0:9 offset1:8
	ds_read2_b32 v[30:31], v222 offset0:3 offset1:2
	ds_read2_b32 v[32:33], v222 offset0:1 offset1:0
	s_waitcnt lgkmcnt(11)
	v_mfma_f32_32x32x16_bf16 v[172:187], v[2:5], v[98:101], 0
	ds_read_b128 v[2:5], v152 offset:4608
	s_waitcnt lgkmcnt(11)
	v_mfma_f32_32x32x16_bf16 v[172:187], v[6:9], v[102:105], v[172:187]
	ds_read_b128 v[6:9], v152 offset:4640
	s_waitcnt lgkmcnt(11)
	v_mfma_f32_32x32x16_bf16 v[172:187], v[10:13], v[106:109], v[172:187]
	ds_read_b128 v[10:13], v152 offset:4672
	s_waitcnt lgkmcnt(11)
	v_mfma_f32_32x32x16_bf16 v[172:187], v[14:17], v[110:113], v[172:187]
	ds_read_b128 v[14:17], v152 offset:4704
	s_waitcnt lgkmcnt(3)
	v_mfma_f32_32x32x16_bf16 v[188:203], v[2:5], v[98:101], 0
	ds_read_b128 v[2:5], v152 offset:9216
	s_waitcnt lgkmcnt(3)
	v_mfma_f32_32x32x16_bf16 v[188:203], v[6:9], v[102:105], v[188:203]
	ds_read_b128 v[6:9], v152 offset:9248
	s_waitcnt lgkmcnt(3)
	v_mfma_f32_32x32x16_bf16 v[188:203], v[10:13], v[106:109], v[188:203]
	ds_read_b128 v[10:13], v152 offset:9280
	s_waitcnt lgkmcnt(3)
	v_mfma_f32_32x32x16_bf16 v[188:203], v[14:17], v[110:113], v[188:203]
	ds_read_b128 v[14:17], v152 offset:9312
	v_add_f32_e32 v172, v172, v18
	v_add_f32_e32 v173, v173, v19
	v_add_f32_e32 v174, v174, v20
	v_add_f32_e32 v175, v175, v21
	v_add_f32_e32 v176, v176, v22
	v_add_f32_e32 v177, v177, v23
	v_add_f32_e32 v178, v178, v24
	v_add_f32_e32 v179, v179, v25
	v_add_f32_e32 v180, v180, v26
	v_add_f32_e32 v181, v181, v27
	v_add_f32_e32 v182, v182, v28
	v_add_f32_e32 v183, v183, v29
	v_add_f32_e32 v184, v184, v30
	v_add_f32_e32 v185, v185, v31
	v_add_f32_e32 v186, v186, v32
	v_add_f32_e32 v187, v187, v33
	v_add_u32_e32 v222, 0x1b194, v147
	ds_read2_b32 v[18:19], v222 offset0:27 offset1:26
	ds_read2_b32 v[20:21], v222 offset0:25 offset1:24
	ds_read2_b32 v[22:23], v222 offset0:19 offset1:18
	ds_read2_b32 v[24:25], v222 offset0:17 offset1:16
	ds_read2_b32 v[26:27], v222 offset0:11 offset1:10
	ds_read2_b32 v[28:29], v222 offset0:9 offset1:8
	ds_read2_b32 v[30:31], v222 offset0:3 offset1:2
	ds_read2_b32 v[32:33], v222 offset0:1 offset1:0
	v_max3_f32 v170, v172, v173, v174
	v_max3_f32 v170, v170, v175, v176
	v_max3_f32 v170, v170, v177, v178
	v_max3_f32 v170, v170, v179, v180
	v_max3_f32 v170, v170, v181, v182
	v_max3_f32 v170, v170, v183, v184
	v_max3_f32 v170, v170, v185, v186
	v_max_f32_e32 v170, v170, v187
	s_waitcnt lgkmcnt(11)
	v_mfma_f32_32x32x16_bf16 v[204:219], v[2:5], v[98:101], 0
	ds_read_b128 v[2:5], v152 offset:13824
	s_waitcnt lgkmcnt(11)
	v_mfma_f32_32x32x16_bf16 v[204:219], v[6:9], v[102:105], v[204:219]
	ds_read_b128 v[6:9], v152 offset:13856
	s_waitcnt lgkmcnt(11)
	v_mfma_f32_32x32x16_bf16 v[204:219], v[10:13], v[106:109], v[204:219]
	ds_read_b128 v[10:13], v152 offset:13888
	s_waitcnt lgkmcnt(11)
	v_mfma_f32_32x32x16_bf16 v[204:219], v[14:17], v[110:113], v[204:219]
	ds_read_b128 v[14:17], v152 offset:13920
	s_waitcnt lgkmcnt(4)
	v_add_f32_e32 v188, v188, v18
	v_add_f32_e32 v189, v189, v19
	v_add_f32_e32 v190, v190, v20
	v_add_f32_e32 v191, v191, v21
	v_add_f32_e32 v192, v192, v22
	v_add_f32_e32 v193, v193, v23
	v_add_f32_e32 v194, v194, v24
	v_add_f32_e32 v195, v195, v25
	v_add_f32_e32 v196, v196, v26
	v_add_f32_e32 v197, v197, v27
	v_add_f32_e32 v198, v198, v28
	v_add_f32_e32 v199, v199, v29
	v_add_f32_e32 v200, v200, v30
	v_add_f32_e32 v201, v201, v31
	v_add_f32_e32 v202, v202, v32
	v_add_f32_e32 v203, v203, v33
	v_add_u32_e32 v222, 0x1b114, v147
	ds_read2_b32 v[18:19], v222 offset0:27 offset1:26
	ds_read2_b32 v[20:21], v222 offset0:25 offset1:24
	ds_read2_b32 v[22:23], v222 offset0:19 offset1:18
	ds_read2_b32 v[24:25], v222 offset0:17 offset1:16
	ds_read2_b32 v[26:27], v222 offset0:11 offset1:10
	ds_read2_b32 v[28:29], v222 offset0:9 offset1:8
	ds_read2_b32 v[30:31], v222 offset0:3 offset1:2
	ds_read2_b32 v[32:33], v222 offset0:1 offset1:0
	v_max3_f32 v171, v188, v189, v190
	v_max3_f32 v171, v171, v191, v192
	v_max3_f32 v171, v171, v193, v194
	v_max3_f32 v171, v171, v195, v196
	v_max3_f32 v171, v171, v197, v198
	v_max3_f32 v171, v171, v199, v200
	v_max3_f32 v171, v171, v201, v202
	v_max_f32_e32 v171, v171, v203
	s_waitcnt lgkmcnt(11)
	v_mfma_f32_32x32x16_bf16 v[154:169], v[2:5], v[98:101], 0
	ds_read_b128 v[2:5], v152 offset:18432
	s_waitcnt lgkmcnt(11)
	v_mfma_f32_32x32x16_bf16 v[154:169], v[6:9], v[102:105], v[154:169]
	ds_read_b128 v[6:9], v152 offset:18464
	s_waitcnt lgkmcnt(11)
	v_mfma_f32_32x32x16_bf16 v[154:169], v[10:13], v[106:109], v[154:169]
	ds_read_b128 v[10:13], v152 offset:18496
	s_waitcnt lgkmcnt(11)
; #define LAS __attribute__((address_space(3)))
; #define MFMA32(a, b, c) __builtin_amdgcn_mfma_f32_32x32x16_bf16((a), (b), (c), 0, 0, 0)
; DI void dil_compute(LAS char* lds, const DilU& u, const LAS float* tbl, int tid, const bf16x8 (&qf)[4]) {
;     ...
;     for (int a = 0; a < 5; ++a) {
;         const int s = w + a;
;         if (32 * s < u.row_lo) continue;
;         const LAS char* Kt = lds + DIL_KB + 32 * s * DIL_PITCH; const LAS char* Vt = lds + DIL_VB + 32 * s * DIL_PITCH;
;         f32x16 p;
; #pragma unroll
;         for (int r = 0; r < 16; ++r) p[r] = 0.f;
; #pragma unroll
;         for (int d0 = 0; d0 < 4; ++d0) { const bf16x8 kf = frag_row(Kt, DIL_PITCH, 0, 16 * d0, lane); p = MFMA32(kf, qf[d0], p); }
;         { const LAS float* tb = tbl + (32 + 128 + r32 - 32 * a - 4 * hi);
; #pragma unroll
;           for (int r = 0; r < 16; ++r) p[r] += tb[-((r & 3) + 8 * (r >> 2))]; }
;         float mx = p[0];
; #pragma unroll
;         for (int r = 1; r < 16; ++r) mx = fmaxf(mx, p[r]);
	v_mfma_f32_32x32x16_bf16 v[154:169], v[14:17], v[110:113], v[154:169]
	ds_read_b128 v[14:17], v152 offset:18528
	s_waitcnt lgkmcnt(4)
	v_add_f32_e32 v204, v204, v18
	v_add_f32_e32 v205, v205, v19
	v_add_f32_e32 v206, v206, v20
	v_add_f32_e32 v207, v207, v21
	v_add_f32_e32 v208, v208, v22
	v_add_f32_e32 v209, v209, v23
	v_add_f32_e32 v210, v210, v24
	v_add_f32_e32 v211, v211, v25
	v_add_f32_e32 v212, v212, v26
	v_add_f32_e32 v213, v213, v27
	v_add_f32_e32 v214, v214, v28
	v_add_f32_e32 v215, v215, v29
	v_add_f32_e32 v216, v216, v30
	v_add_f32_e32 v217, v217, v31
	v_add_f32_e32 v218, v218, v32
	v_add_f32_e32 v219, v219, v33
	v_add_u32_e32 v222, 0x1b094, v147
	ds_read2_b32 v[18:19], v222 offset0:27 offset1:26
	ds_read2_b32 v[20:21], v222 offset0:25 offset1:24
	ds_read2_b32 v[22:23], v222 offset0:19 offset1:18
	ds_read2_b32 v[24:25], v222 offset0:17 offset1:16
	ds_read2_b32 v[26:27], v222 offset0:11 offset1:10
	ds_read2_b32 v[28:29], v222 offset0:9 offset1:8
	ds_read2_b32 v[30:31], v222 offset0:3 offset1:2
	ds_read2_b32 v[32:33], v222 offset0:1 offset1:0
	v_max3_f32 v220, v204, v205, v206
	v_max3_f32 v220, v220, v207, v208
	v_max3_f32 v220, v220, v209, v210
	v_max3_f32 v220, v220, v211, v212
	v_max3_f32 v220, v220, v213, v214
	v_max3_f32 v220, v220, v215, v216
	v_max3_f32 v220, v220, v217, v218
	v_max_f32_e32 v220, v220, v219
	s_waitcnt lgkmcnt(11)
	v_mfma_f32_32x32x16_bf16 v[34:49], v[2:5], v[98:101], 0
	s_waitcnt lgkmcnt(10)
	v_mfma_f32_32x32x16_bf16 v[34:49], v[6:9], v[102:105], v[34:49]
	s_waitcnt lgkmcnt(9)
	v_mfma_f32_32x32x16_bf16 v[34:49], v[10:13], v[106:109], v[34:49]
	s_waitcnt lgkmcnt(8)
	v_mfma_f32_32x32x16_bf16 v[34:49], v[14:17], v[110:113], v[34:49]
	s_waitcnt lgkmcnt(0)
	v_add_u32_e32 v222, 0x1b014, v147
	ds_read2_b32 v[2:3], v222 offset0:27 offset1:26
	ds_read2_b32 v[4:5], v222 offset0:25 offset1:24
	ds_read2_b32 v[6:7], v222 offset0:19 offset1:18
	ds_read2_b32 v[8:9], v222 offset0:17 offset1:16
	ds_read2_b32 v[10:11], v222 offset0:11 offset1:10
	ds_read2_b32 v[12:13], v222 offset0:9 offset1:8
	ds_read2_b32 v[14:15], v222 offset0:3 offset1:2
	ds_read2_b32 v[16:17], v222 offset0:1 offset1:0
	v_add_f32_e32 v154, v154, v18
	v_add_f32_e32 v155, v155, v19
	v_add_f32_e32 v156, v156, v20
	v_add_f32_e32 v157, v157, v21
	v_add_f32_e32 v158, v158, v22
	v_add_f32_e32 v159, v159, v23
	v_add_f32_e32 v160, v160, v24
	v_add_f32_e32 v161, v161, v25
	v_add_f32_e32 v162, v162, v26
	v_add_f32_e32 v163, v163, v27
	v_add_f32_e32 v164, v164, v28
	v_add_f32_e32 v165, v165, v29
	v_add_f32_e32 v166, v166, v30
	v_add_f32_e32 v167, v167, v31
	v_add_f32_e32 v168, v168, v32
	v_add_f32_e32 v169, v169, v33
	v_max3_f32 v221, v154, v155, v156
	v_max3_f32 v221, v221, v157, v158
	v_max3_f32 v221, v221, v159, v160
	v_max3_f32 v221, v221, v161, v162
	v_max3_f32 v221, v221, v163, v164
	v_max3_f32 v221, v221, v165, v166
	v_max3_f32 v221, v221, v167, v168
	v_max_f32_e32 v221, v221, v169
	s_waitcnt lgkmcnt(0)
	v_add_f32_e32 v34, v34, v2
	v_add_f32_e32 v35, v35, v3
	v_add_f32_e32 v36, v36, v4
	v_add_f32_e32 v37, v37, v5
	v_add_f32_e32 v38, v38, v6
	v_add_f32_e32 v39, v39, v7
	v_add_f32_e32 v40, v40, v8
	v_add_f32_e32 v41, v41, v9
	v_add_f32_e32 v42, v42, v10
	v_add_f32_e32 v43, v43, v11
	v_add_f32_e32 v44, v44, v12
	v_add_f32_e32 v45, v45, v13
	v_add_f32_e32 v46, v46, v14
	v_add_f32_e32 v47, v47, v15
	v_add_f32_e32 v48, v48, v16
	v_add_f32_e32 v49, v49, v17
	v_max3_f32 v223, v34, v35, v36
	v_max3_f32 v223, v223, v37, v38
	v_max3_f32 v223, v223, v39, v40
	v_max3_f32 v223, v223, v41, v42
	v_max3_f32 v223, v223, v43, v44
	v_max3_f32 v223, v223, v45, v46
	v_max3_f32 v223, v223, v47, v48
	v_max_f32_e32 v223, v223, v49
	s_cmp_lt_i32 s10, s4
	s_cbranch_scc0 .Ldil_nomask
	v_mov_b32_e32 v170, 0xff800000
	v_mov_b32_e32 v172, v170
	v_mov_b32_e32 v173, v170
	v_mov_b32_e32 v174, v170
	v_mov_b32_e32 v175, v170
	v_mov_b32_e32 v176, v170
	v_mov_b32_e32 v177, v170
	v_mov_b32_e32 v178, v170
	v_mov_b32_e32 v179, v170
	v_mov_b32_e32 v180, v170
	v_mov_b32_e32 v181, v170
	v_mov_b32_e32 v182, v170
	v_mov_b32_e32 v183, v170
	v_mov_b32_e32 v184, v170
	v_mov_b32_e32 v185, v170
	v_mov_b32_e32 v186, v170
	v_mov_b32_e32 v187, v170
	s_add_i32 s98, s10, 32
	s_cmp_lt_i32 s98, s4
	s_cbranch_scc0 .Ldil_nomask
	v_mov_b32_e32 v171, 0xff800000
	v_mov_b32_e32 v188, v171
	v_mov_b32_e32 v189, v171
	v_mov_b32_e32 v190, v171
	v_mov_b32_e32 v191, v171
	v_mov_b32_e32 v192, v171
	v_mov_b32_e32 v193, v171
	v_mov_b32_e32 v194, v171
	v_mov_b32_e32 v195, v171
	v_mov_b32_e32 v196, v171
	v_mov_b32_e32 v197, v171
	v_mov_b32_e32 v198, v171
	v_mov_b32_e32 v199, v171
	v_mov_b32_e32 v200, v171
	v_mov_b32_e32 v201, v171
	v_mov_b32_e32 v202, v171
	v_mov_b32_e32 v203, v171
	s_add_i32 s98, s10, 64
	s_cmp_lt_i32 s98, s4
	s_cbranch_scc0 .Ldil_nomask
	v_mov_b32_e32 v220, 0xff800000
	v_mov_b32_e32 v204, v220
	v_mov_b32_e32 v205, v220
	v_mov_b32_e32 v206, v220
	v_mov_b32_e32 v207, v220
	v_mov_b32_e32 v208, v220
	v_mov_b32_e32 v209, v220
	v_mov_b32_e32 v210, v220
	v_mov_b32_e32 v211, v220
	v_mov_b32_e32 v212, v220
	v_mov_b32_e32 v213, v220
	v_mov_b32_e32 v214, v220
	v_mov_b32_e32 v215, v220
	v_mov_b32_e32 v216, v220
	v_mov_b32_e32 v217, v220
	v_mov_b32_e32 v218, v220
	v_mov_b32_e32 v219, v220
	s_add_i32 s98, s10, 96
	s_cmp_lt_i32 s98, s4
	s_cbranch_scc0 .Ldil_nomask
	v_mov_b32_e32 v221, 0xff800000
	v_mov_b32_e32 v154, v221
	v_mov_b32_e32 v155, v221
	v_mov_b32_e32 v156, v221
	v_mov_b32_e32 v157, v221
	v_mov_b32_e32 v158, v221
	v_mov_b32_e32 v159, v221
	v_mov_b32_e32 v160, v221
	v_mov_b32_e32 v161, v221
	v_mov_b32_e32 v162, v221
	v_mov_b32_e32 v163, v221
	v_mov_b32_e32 v164, v221
	v_mov_b32_e32 v165, v221
	v_mov_b32_e32 v166, v221
	v_mov_b32_e32 v167, v221
	v_mov_b32_e32 v168, v221
	v_mov_b32_e32 v169, v221
; #define MFMA32(a, b, c) __builtin_amdgcn_mfma_f32_32x32x16_bf16((a), (b), (c), 0, 0, 0)
; DI bf16x8 pack8(const f32x16& x, int s) { u32x4 p; p[0] = cvtpk(x[8 * s], x[8 * s + 1]); p[1] = cvtpk(x[8 * s + 2], x[8 * s + 3]); p[2] = cvtpk(x[8 * s + 4], x[8 * s + 5]); p[3] = cvtpk(x[8 * s + 6], x[8 * s + 7]); return __builtin_bit_cast(bf16x8, p); }
; DI void dil_compute(LAS char* lds, const DilU& u, const LAS float* tbl, int tid, const bf16x8 (&qf)[4]) {
;     ...
;         float mx = p[0];
; #pragma unroll
;         for (int r = 1; r < 16; ++r) mx = fmaxf(mx, p[r]);
;         mx = fmaxf(mx, __shfl_xor(mx, 32));
;         const float mn = fmaxf(m, mx);
;         if (__any(mn > m)) {
;             const float mr_ = (mn == -INFINITY) ? 0.f : mn;
;             const float alpha = __builtin_amdgcn_exp2f(m - mr_);
;             l *= alpha;
; #pragma unroll
;             for (int i = 0; i < 2; ++i)
; #pragma unroll
;                 for (int r = 0; r < 16; ++r) o[i][r] *= alpha;
;             m = mn;
;         }
;         const float mref = (m == -INFINITY) ? 0.f : m;
; #pragma unroll
;         for (int r = 0; r < 16; ++r) { p[r] = __builtin_amdgcn_exp2f(p[r] - mref); l += p[r]; }
;         const bf16x8 pb0 = pack8(p, 0), pb1 = pack8(p, 1);
; #pragma unroll
;         for (int db = 0; db < 2; ++db) {
;             const bf16x8 v0 = frag_tr_perm(Vt, DIL_PITCH, 0, 32 * db, lane), v1 = frag_tr_perm(Vt, DIL_PITCH, 16, 32 * db, lane);
;             o[db] = MFMA32(v0, pb0, o[db]); o[db] = MFMA32(v1, pb1, o[db]);
;         }
.Ldil_nomask:
	v_max3_f32 v145, v170, v171, v220
	v_max3_f32 v145, v145, v221, v223
	ds_bpermute_b32 v222, v133, v145
	v_mov_b32_e32 v221, 0xff800000
	s_waitcnt lgkmcnt(0)
	v_max_f32_e32 v145, v145, v222
	v_cmp_neq_f32_e32 vcc, v145, v221
	s_nop 1
	v_cndmask_b32_e32 v170, 0, v145, vcc
	v_sub_f32_e32 v172, v172, v170
	v_sub_f32_e32 v173, v173, v170
	v_sub_f32_e32 v174, v174, v170
	v_sub_f32_e32 v175, v175, v170
	v_sub_f32_e32 v176, v176, v170
	v_sub_f32_e32 v177, v177, v170
	v_sub_f32_e32 v178, v178, v170
	v_sub_f32_e32 v179, v179, v170
	v_sub_f32_e32 v180, v180, v170
	v_sub_f32_e32 v181, v181, v170
	v_sub_f32_e32 v182, v182, v170
	v_sub_f32_e32 v183, v183, v170
	v_sub_f32_e32 v184, v184, v170
	v_sub_f32_e32 v185, v185, v170
	v_sub_f32_e32 v186, v186, v170
	v_sub_f32_e32 v187, v187, v170
	v_exp_f32_e32 v172, v172
	v_exp_f32_e32 v173, v173
	v_exp_f32_e32 v174, v174
	v_exp_f32_e32 v175, v175
	v_exp_f32_e32 v176, v176
	v_exp_f32_e32 v177, v177
	v_exp_f32_e32 v178, v178
	v_exp_f32_e32 v179, v179
	v_exp_f32_e32 v180, v180
	v_exp_f32_e32 v181, v181
	v_exp_f32_e32 v182, v182
	v_exp_f32_e32 v183, v183
	v_exp_f32_e32 v184, v184
	v_exp_f32_e32 v185, v185
	v_exp_f32_e32 v186, v186
	v_exp_f32_e32 v187, v187
	v_add_f32_e32 v171, v172, v174
	v_add_f32_e32 v220, v173, v175
	v_add_f32_e32 v171, v171, v176
	v_add_f32_e32 v220, v220, v177
	v_add_f32_e32 v171, v171, v178
	v_add_f32_e32 v220, v220, v179
	v_add_f32_e32 v171, v171, v180
	v_add_f32_e32 v220, v220, v181
	v_add_f32_e32 v171, v171, v182
	v_add_f32_e32 v220, v220, v183
	v_add_f32_e32 v171, v171, v184
	v_add_f32_e32 v220, v220, v185
	v_add_f32_e32 v171, v171, v186
	v_add_f32_e32 v220, v220, v187
	v_cvt_pk_bf16_f32 v98, v172, v173
	v_cvt_pk_bf16_f32 v99, v174, v175
	v_cvt_pk_bf16_f32 v100, v176, v177
	v_cvt_pk_bf16_f32 v101, v178, v179
	v_cvt_pk_bf16_f32 v102, v180, v181
	v_cvt_pk_bf16_f32 v103, v182, v183
	v_cvt_pk_bf16_f32 v104, v184, v185
	v_cvt_pk_bf16_f32 v105, v186, v187
	v_add_u32_e32 v222, 0, v153
	ds_read_b64_tr_b16 v[172:173], v222 offset:55296
	ds_read_b64_tr_b16 v[174:175], v222 offset:56448
	ds_read_b64_tr_b16 v[176:177], v222 offset:57600
	ds_read_b64_tr_b16 v[178:179], v222 offset:58752
	ds_read_b64_tr_b16 v[180:181], v222 offset:55360
	ds_read_b64_tr_b16 v[182:183], v222 offset:56512
	ds_read_b64_tr_b16 v[184:185], v222 offset:57664
	ds_read_b64_tr_b16 v[186:187], v222 offset:58816
	v_sub_f32_e32 v188, v188, v170
	v_sub_f32_e32 v189, v189, v170
	v_sub_f32_e32 v190, v190, v170
	v_sub_f32_e32 v191, v191, v170
	v_sub_f32_e32 v192, v192, v170
	v_sub_f32_e32 v193, v193, v170
	v_sub_f32_e32 v194, v194, v170
	v_sub_f32_e32 v195, v195, v170
	v_sub_f32_e32 v196, v196, v170
	v_sub_f32_e32 v197, v197, v170
	v_sub_f32_e32 v198, v198, v170
	v_sub_f32_e32 v199, v199, v170
	v_sub_f32_e32 v200, v200, v170
	v_sub_f32_e32 v201, v201, v170
	v_sub_f32_e32 v202, v202, v170
	v_sub_f32_e32 v203, v203, v170
	v_exp_f32_e32 v188, v188
	v_exp_f32_e32 v189, v189
	v_exp_f32_e32 v190, v190
	v_exp_f32_e32 v191, v191
	v_exp_f32_e32 v192, v192
	v_exp_f32_e32 v193, v193
	v_exp_f32_e32 v194, v194
	v_exp_f32_e32 v195, v195
	v_exp_f32_e32 v196, v196
	v_exp_f32_e32 v197, v197
	v_exp_f32_e32 v198, v198
	v_exp_f32_e32 v199, v199
	v_exp_f32_e32 v200, v200
	v_exp_f32_e32 v201, v201
	v_exp_f32_e32 v202, v202
	v_exp_f32_e32 v203, v203
	v_add_f32_e32 v171, v171, v188
	v_add_f32_e32 v220, v220, v189
	v_add_f32_e32 v171, v171, v190
	v_add_f32_e32 v220, v220, v191
	v_add_f32_e32 v171, v171, v192
	v_add_f32_e32 v220, v220, v193
	v_add_f32_e32 v171, v171, v194
	v_add_f32_e32 v220, v220, v195
	v_add_f32_e32 v171, v171, v196
	v_add_f32_e32 v220, v220, v197
	v_add_f32_e32 v171, v171, v198
	v_add_f32_e32 v220, v220, v199
	v_add_f32_e32 v171, v171, v200
	v_add_f32_e32 v220, v220, v201
	v_add_f32_e32 v171, v171, v202
	v_add_f32_e32 v220, v220, v203
	v_cvt_pk_bf16_f32 v106, v188, v189
	v_cvt_pk_bf16_f32 v107, v190, v191
	v_cvt_pk_bf16_f32 v108, v192, v193
	v_cvt_pk_bf16_f32 v109, v194, v195
	v_cvt_pk_bf16_f32 v110, v196, v197
	v_cvt_pk_bf16_f32 v111, v198, v199
	v_cvt_pk_bf16_f32 v112, v200, v201
	v_cvt_pk_bf16_f32 v113, v202, v203
	s_waitcnt lgkmcnt(6)
	v_mfma_f32_32x32x16_bf16 v[18:33], v[172:175], v[98:101], 0
	s_waitcnt lgkmcnt(4)
	v_mfma_f32_32x32x16_bf16 v[18:33], v[176:179], v[102:105], v[18:33]
	s_waitcnt lgkmcnt(2)
	v_mfma_f32_32x32x16_bf16 v[2:17], v[180:183], v[98:101], 0
	s_waitcnt lgkmcnt(0)
	v_mfma_f32_32x32x16_bf16 v[2:17], v[184:187], v[102:105], v[2:17]
	v_add_u32_e32 v222, 4608, v153
	ds_read_b64_tr_b16 v[188:189], v222 offset:55296
	ds_read_b64_tr_b16 v[190:191], v222 offset:56448
	ds_read_b64_tr_b16 v[192:193], v222 offset:57600
	ds_read_b64_tr_b16 v[194:195], v222 offset:58752
	ds_read_b64_tr_b16 v[196:197], v222 offset:55360
	ds_read_b64_tr_b16 v[198:199], v222 offset:56512
	ds_read_b64_tr_b16 v[200:201], v222 offset:57664
	ds_read_b64_tr_b16 v[202:203], v222 offset:58816
	v_sub_f32_e32 v204, v204, v170
	v_sub_f32_e32 v205, v205, v170
	v_sub_f32_e32 v206, v206, v170
	v_sub_f32_e32 v207, v207, v170
	v_sub_f32_e32 v208, v208, v170
	v_sub_f32_e32 v209, v209, v170
	v_sub_f32_e32 v210, v210, v170
	v_sub_f32_e32 v211, v211, v170
	v_sub_f32_e32 v212, v212, v170
	v_sub_f32_e32 v213, v213, v170
	v_sub_f32_e32 v214, v214, v170
	v_sub_f32_e32 v215, v215, v170
	v_sub_f32_e32 v216, v216, v170
	v_sub_f32_e32 v217, v217, v170
	v_sub_f32_e32 v218, v218, v170
	v_sub_f32_e32 v219, v219, v170
	v_exp_f32_e32 v204, v204
	v_exp_f32_e32 v205, v205
	v_exp_f32_e32 v206, v206
	v_exp_f32_e32 v207, v207
	v_exp_f32_e32 v208, v208
	v_exp_f32_e32 v209, v209
	v_exp_f32_e32 v210, v210
	v_exp_f32_e32 v211, v211
	v_exp_f32_e32 v212, v212
	v_exp_f32_e32 v213, v213
	v_exp_f32_e32 v214, v214
	v_exp_f32_e32 v215, v215
	v_exp_f32_e32 v216, v216
	v_exp_f32_e32 v217, v217
	v_exp_f32_e32 v218, v218
	v_exp_f32_e32 v219, v219
	v_add_f32_e32 v171, v171, v204
	v_add_f32_e32 v220, v220, v205
	v_add_f32_e32 v171, v171, v206
	v_add_f32_e32 v220, v220, v207
	v_add_f32_e32 v171, v171, v208
	v_add_f32_e32 v220, v220, v209
	v_add_f32_e32 v171, v171, v210
	v_add_f32_e32 v220, v220, v211
	v_add_f32_e32 v171, v171, v212
	v_add_f32_e32 v220, v220, v213
	v_add_f32_e32 v171, v171, v214
	v_add_f32_e32 v220, v220, v215
	v_add_f32_e32 v171, v171, v216
	v_add_f32_e32 v220, v220, v217
	v_add_f32_e32 v171, v171, v218
	v_add_f32_e32 v220, v220, v219
	v_cvt_pk_bf16_f32 v98, v204, v205
	v_cvt_pk_bf16_f32 v99, v206, v207
	v_cvt_pk_bf16_f32 v100, v208, v209
	v_cvt_pk_bf16_f32 v101, v210, v211
	v_cvt_pk_bf16_f32 v102, v212, v213
	v_cvt_pk_bf16_f32 v103, v214, v215
	v_cvt_pk_bf16_f32 v104, v216, v217
	v_cvt_pk_bf16_f32 v105, v218, v219
	s_waitcnt lgkmcnt(6)
; #define MFMA32(a, b, c) __builtin_amdgcn_mfma_f32_32x32x16_bf16((a), (b), (c), 0, 0, 0)
; DI bf16x8 pack8(const f32x16& x, int s) { u32x4 p; p[0] = cvtpk(x[8 * s], x[8 * s + 1]); p[1] = cvtpk(x[8 * s + 2], x[8 * s + 3]); p[2] = cvtpk(x[8 * s + 4], x[8 * s + 5]); p[3] = cvtpk(x[8 * s + 6], x[8 * s + 7]); return __builtin_bit_cast(bf16x8, p); }
; DI void dil_compute(LAS char* lds, const DilU& u, const LAS float* tbl, int tid, const bf16x8 (&qf)[4]) {
;     ...
;         const float mref = (m == -INFINITY) ? 0.f : m;
; #pragma unroll
;         for (int r = 0; r < 16; ++r) { p[r] = __builtin_amdgcn_exp2f(p[r] - mref); l += p[r]; }
;         const bf16x8 pb0 = pack8(p, 0), pb1 = pack8(p, 1);
; #pragma unroll
;         for (int db = 0; db < 2; ++db) {
;             const bf16x8 v0 = frag_tr_perm(Vt, DIL_PITCH, 0, 32 * db, lane), v1 = frag_tr_perm(Vt, DIL_PITCH, 16, 32 * db, lane);
;             o[db] = MFMA32(v0, pb0, o[db]); o[db] = MFMA32(v1, pb1, o[db]);
;         }
	v_mfma_f32_32x32x16_bf16 v[18:33], v[188:191], v[106:109], v[18:33]
	s_waitcnt lgkmcnt(4)
	v_mfma_f32_32x32x16_bf16 v[18:33], v[192:195], v[110:113], v[18:33]
	s_waitcnt lgkmcnt(2)
	v_mfma_f32_32x32x16_bf16 v[2:17], v[196:199], v[106:109], v[2:17]
	s_waitcnt lgkmcnt(0)
	v_mfma_f32_32x32x16_bf16 v[2:17], v[200:203], v[110:113], v[2:17]
	v_add_u32_e32 v222, 9216, v153
	ds_read_b64_tr_b16 v[204:205], v222 offset:55296
	ds_read_b64_tr_b16 v[206:207], v222 offset:56448
	ds_read_b64_tr_b16 v[208:209], v222 offset:57600
	ds_read_b64_tr_b16 v[210:211], v222 offset:58752
	ds_read_b64_tr_b16 v[212:213], v222 offset:55360
	ds_read_b64_tr_b16 v[214:215], v222 offset:56512
	ds_read_b64_tr_b16 v[216:217], v222 offset:57664
	ds_read_b64_tr_b16 v[218:219], v222 offset:58816
	v_sub_f32_e32 v154, v154, v170
	v_sub_f32_e32 v155, v155, v170
	v_sub_f32_e32 v156, v156, v170
	v_sub_f32_e32 v157, v157, v170
	v_sub_f32_e32 v158, v158, v170
	v_sub_f32_e32 v159, v159, v170
	v_sub_f32_e32 v160, v160, v170
	v_sub_f32_e32 v161, v161, v170
	v_sub_f32_e32 v162, v162, v170
	v_sub_f32_e32 v163, v163, v170
	v_sub_f32_e32 v164, v164, v170
	v_sub_f32_e32 v165, v165, v170
	v_sub_f32_e32 v166, v166, v170
	v_sub_f32_e32 v167, v167, v170
	v_sub_f32_e32 v168, v168, v170
	v_sub_f32_e32 v169, v169, v170
	v_exp_f32_e32 v154, v154
	v_exp_f32_e32 v155, v155
	v_exp_f32_e32 v156, v156
	v_exp_f32_e32 v157, v157
	v_exp_f32_e32 v158, v158
	v_exp_f32_e32 v159, v159
	v_exp_f32_e32 v160, v160
	v_exp_f32_e32 v161, v161
	v_exp_f32_e32 v162, v162
	v_exp_f32_e32 v163, v163
	v_exp_f32_e32 v164, v164
	v_exp_f32_e32 v165, v165
	v_exp_f32_e32 v166, v166
	v_exp_f32_e32 v167, v167
	v_exp_f32_e32 v168, v168
	v_exp_f32_e32 v169, v169
	v_add_f32_e32 v171, v171, v154
	v_add_f32_e32 v220, v220, v155
	v_add_f32_e32 v171, v171, v156
	v_add_f32_e32 v220, v220, v157
	v_add_f32_e32 v171, v171, v158
	v_add_f32_e32 v220, v220, v159
	v_add_f32_e32 v171, v171, v160
	v_add_f32_e32 v220, v220, v161
	v_add_f32_e32 v171, v171, v162
	v_add_f32_e32 v220, v220, v163
	v_add_f32_e32 v171, v171, v164
	v_add_f32_e32 v220, v220, v165
	v_add_f32_e32 v171, v171, v166
	v_add_f32_e32 v220, v220, v167
	v_add_f32_e32 v171, v171, v168
	v_add_f32_e32 v220, v220, v169
	v_cvt_pk_bf16_f32 v106, v154, v155
	v_cvt_pk_bf16_f32 v107, v156, v157
	v_cvt_pk_bf16_f32 v108, v158, v159
	v_cvt_pk_bf16_f32 v109, v160, v161
	v_cvt_pk_bf16_f32 v110, v162, v163
	v_cvt_pk_bf16_f32 v111, v164, v165
	v_cvt_pk_bf16_f32 v112, v166, v167
	v_cvt_pk_bf16_f32 v113, v168, v169
	s_waitcnt lgkmcnt(6)
	v_mfma_f32_32x32x16_bf16 v[18:33], v[204:207], v[98:101], v[18:33]
	s_waitcnt lgkmcnt(4)
	v_mfma_f32_32x32x16_bf16 v[18:33], v[208:211], v[102:105], v[18:33]
	s_waitcnt lgkmcnt(2)
	v_mfma_f32_32x32x16_bf16 v[2:17], v[212:215], v[98:101], v[2:17]
	s_waitcnt lgkmcnt(0)
	v_mfma_f32_32x32x16_bf16 v[2:17], v[216:219], v[102:105], v[2:17]
	v_add_u32_e32 v222, 13824, v153
	ds_read_b64_tr_b16 v[154:155], v222 offset:55296
	ds_read_b64_tr_b16 v[156:157], v222 offset:56448
	ds_read_b64_tr_b16 v[158:159], v222 offset:57600
	ds_read_b64_tr_b16 v[160:161], v222 offset:58752
	ds_read_b64_tr_b16 v[162:163], v222 offset:55360
	ds_read_b64_tr_b16 v[164:165], v222 offset:56512
	ds_read_b64_tr_b16 v[166:167], v222 offset:57664
	ds_read_b64_tr_b16 v[168:169], v222 offset:58816
	v_sub_f32_e32 v34, v34, v170
	v_sub_f32_e32 v35, v35, v170
	v_sub_f32_e32 v36, v36, v170
	v_sub_f32_e32 v37, v37, v170
	v_sub_f32_e32 v38, v38, v170
	v_sub_f32_e32 v39, v39, v170
	v_sub_f32_e32 v40, v40, v170
	v_sub_f32_e32 v41, v41, v170
	v_sub_f32_e32 v42, v42, v170
	v_sub_f32_e32 v43, v43, v170
	v_sub_f32_e32 v44, v44, v170
	v_sub_f32_e32 v45, v45, v170
	v_sub_f32_e32 v46, v46, v170
	v_sub_f32_e32 v47, v47, v170
	v_sub_f32_e32 v48, v48, v170
	v_sub_f32_e32 v49, v49, v170
	v_exp_f32_e32 v34, v34
	v_exp_f32_e32 v35, v35
	v_exp_f32_e32 v36, v36
	v_exp_f32_e32 v37, v37
	v_exp_f32_e32 v38, v38
	v_exp_f32_e32 v39, v39
	v_exp_f32_e32 v40, v40
	v_exp_f32_e32 v41, v41
	v_exp_f32_e32 v42, v42
	v_exp_f32_e32 v43, v43
	v_exp_f32_e32 v44, v44
	v_exp_f32_e32 v45, v45
	v_exp_f32_e32 v46, v46
	v_exp_f32_e32 v47, v47
	v_exp_f32_e32 v48, v48
	v_exp_f32_e32 v49, v49
	v_add_f32_e32 v171, v171, v34
	v_add_f32_e32 v220, v220, v35
	v_add_f32_e32 v171, v171, v36
	v_add_f32_e32 v220, v220, v37
	v_add_f32_e32 v171, v171, v38
	v_add_f32_e32 v220, v220, v39
	v_add_f32_e32 v171, v171, v40
	v_add_f32_e32 v220, v220, v41
	v_add_f32_e32 v171, v171, v42
	v_add_f32_e32 v220, v220, v43
	v_add_f32_e32 v171, v171, v44
	v_add_f32_e32 v220, v220, v45
	v_add_f32_e32 v171, v171, v46
	v_add_f32_e32 v220, v220, v47
	v_add_f32_e32 v171, v171, v48
	v_add_f32_e32 v220, v220, v49
	v_cvt_pk_bf16_f32 v98, v34, v35
	v_cvt_pk_bf16_f32 v99, v36, v37
	v_cvt_pk_bf16_f32 v100, v38, v39
	v_cvt_pk_bf16_f32 v101, v40, v41
	v_cvt_pk_bf16_f32 v102, v42, v43
	v_cvt_pk_bf16_f32 v103, v44, v45
	v_cvt_pk_bf16_f32 v104, v46, v47
	v_cvt_pk_bf16_f32 v105, v48, v49
	s_waitcnt lgkmcnt(6)
; #define MFMA32(a, b, c) __builtin_amdgcn_mfma_f32_32x32x16_bf16((a), (b), (c), 0, 0, 0)
; DI unsigned cvtpk(float lo, float hi) { f32x2_t v = {lo, hi}; bf16x2_t b = __builtin_convertvector(v, bf16x2_t); return __builtin_bit_cast(unsigned, b); }
; DI bf16x8 pack8(const f32x16& x, int s) { u32x4 p; p[0] = cvtpk(x[8 * s], x[8 * s + 1]); p[1] = cvtpk(x[8 * s + 2], x[8 * s + 3]); p[2] = cvtpk(x[8 * s + 4], x[8 * s + 5]); p[3] = cvtpk(x[8 * s + 6], x[8 * s + 7]); return __builtin_bit_cast(bf16x8, p); }
; DI void dil_compute(LAS char* lds, const DilU& u, const LAS float* tbl, int tid, const bf16x8 (&qf)[4]) {
;     ...
;         const bf16x8 pb0 = pack8(p, 0), pb1 = pack8(p, 1);
; #pragma unroll
;         for (int db = 0; db < 2; ++db) {
;             const bf16x8 v0 = frag_tr_perm(Vt, DIL_PITCH, 0, 32 * db, lane), v1 = frag_tr_perm(Vt, DIL_PITCH, 16, 32 * db, lane);
;             o[db] = MFMA32(v0, pb0, o[db]); o[db] = MFMA32(v1, pb1, o[db]);
;         }
;     }
;     l += __shfl_xor(l, 32);
;     const float inv = 1.f / l;
;     bf16* orow = u.Ob + (long)(32 * w + r32) * u.ostride;
; #pragma unroll
;     for (int db = 0; db < 2; ++db)
; #pragma unroll
;         for (int g = 0; g < 4; ++g) { u32x2 wv; wv.x = cvtpk(o[db][4 * g] * inv, o[db][4 * g + 1] * inv); wv.y = cvtpk(o[db][4 * g + 2] * inv, o[db][4 * g + 3] * inv);
;             *(u32x2*)(orow + 32 * db + 8 * g + 4 * hi) = wv; }
;     if (hi == 0) u.lse[(long)(32 * w + r32) * u.lstride] = m + __log2f(l);
	v_mfma_f32_32x32x16_bf16 v[18:33], v[154:157], v[106:109], v[18:33]
	s_waitcnt lgkmcnt(4)
	v_mfma_f32_32x32x16_bf16 v[18:33], v[158:161], v[110:113], v[18:33]
	s_waitcnt lgkmcnt(2)
	v_mfma_f32_32x32x16_bf16 v[2:17], v[162:165], v[106:109], v[2:17]
	s_waitcnt lgkmcnt(0)
	v_mfma_f32_32x32x16_bf16 v[2:17], v[166:169], v[110:113], v[2:17]
	v_add_u32_e32 v222, 18432, v153
	ds_read_b64_tr_b16 v[34:35], v222 offset:55296
	ds_read_b64_tr_b16 v[36:37], v222 offset:56448
	ds_read_b64_tr_b16 v[38:39], v222 offset:57600
	ds_read_b64_tr_b16 v[40:41], v222 offset:58752
	ds_read_b64_tr_b16 v[42:43], v222 offset:55360
	ds_read_b64_tr_b16 v[44:45], v222 offset:56512
	ds_read_b64_tr_b16 v[46:47], v222 offset:57664
	ds_read_b64_tr_b16 v[48:49], v222 offset:58816
	s_waitcnt lgkmcnt(6)
	v_mfma_f32_32x32x16_bf16 v[18:33], v[34:37], v[98:101], v[18:33]
	s_waitcnt lgkmcnt(4)
	v_mfma_f32_32x32x16_bf16 v[18:33], v[38:41], v[102:105], v[18:33]
	s_waitcnt lgkmcnt(2)
	v_mfma_f32_32x32x16_bf16 v[2:17], v[42:45], v[98:101], v[2:17]
	s_waitcnt lgkmcnt(0)
	v_mfma_f32_32x32x16_bf16 v[2:17], v[46:49], v[102:105], v[2:17]
	v_add_f32_e32 v174, v171, v220
	v_or_b32_e32 v172, s10, v131
	ds_bpermute_b32 v173, v133, v174
	v_mov_b32_e32 v147, 0
	v_mul_lo_u32 v178, v172, s6
	v_mov_b32_e32 v179, 0
	v_lshl_add_u64 v[178:179], v[178:179], 1, s[12:13]
	v_lshl_add_u64 v[178:179], v[178:179], 0, v[146:147]
	s_waitcnt lgkmcnt(0)
	v_add_f32_e32 v174, v174, v173
	v_div_scale_f32 v175, s[10:11], v174, v174, 1.0
	v_rcp_f32_e32 v176, v175
	v_div_scale_f32 v177, vcc, 1.0, v174, 1.0
	v_fma_f32 v180, -v175, v176, 1.0
	v_fmac_f32_e32 v176, v180, v176
	v_mul_f32_e32 v180, v177, v176
	v_fma_f32 v181, -v175, v180, v177
	v_fmac_f32_e32 v180, v181, v176
	v_fma_f32 v175, -v175, v180, v177
	v_div_fmas_f32 v175, v175, v176, v180
	v_div_fixup_f32 v176, v175, v174, 1.0
	s_nop 0
	v_mul_f32_e32 v18, v18, v176
	v_mul_f32_e32 v19, v19, v176
	v_mul_f32_e32 v20, v20, v176
	v_mul_f32_e32 v21, v21, v176
	v_cvt_pk_bf16_f32 v18, v18, v19
	v_cvt_pk_bf16_f32 v19, v20, v21
	global_store_dwordx2 v[178:179], v[18:19], off
	v_mul_f32_e32 v2, v2, v176
	v_mul_f32_e32 v3, v3, v176
	v_mul_f32_e32 v4, v4, v176
	v_mul_f32_e32 v5, v5, v176
	v_cvt_pk_bf16_f32 v2, v2, v3
	v_cvt_pk_bf16_f32 v3, v4, v5
	global_store_dwordx2 v[178:179], v[2:3], off offset:64
	v_mul_f32_e32 v22, v22, v176
	v_mul_f32_e32 v23, v23, v176
	v_mul_f32_e32 v24, v24, v176
	v_mul_f32_e32 v25, v25, v176
	v_cvt_pk_bf16_f32 v22, v22, v23
	v_cvt_pk_bf16_f32 v23, v24, v25
	global_store_dwordx2 v[178:179], v[22:23], off offset:16
	v_mul_f32_e32 v6, v6, v176
	v_mul_f32_e32 v7, v7, v176
	v_mul_f32_e32 v8, v8, v176
	v_mul_f32_e32 v9, v9, v176
	v_cvt_pk_bf16_f32 v6, v6, v7
	v_cvt_pk_bf16_f32 v7, v8, v9
	global_store_dwordx2 v[178:179], v[6:7], off offset:80
	v_mul_f32_e32 v26, v26, v176
	v_mul_f32_e32 v27, v27, v176
	v_mul_f32_e32 v28, v28, v176
	v_mul_f32_e32 v29, v29, v176
	v_cvt_pk_bf16_f32 v26, v26, v27
	v_cvt_pk_bf16_f32 v27, v28, v29
	global_store_dwordx2 v[178:179], v[26:27], off offset:32
	v_mul_f32_e32 v10, v10, v176
	v_mul_f32_e32 v11, v11, v176
	v_mul_f32_e32 v12, v12, v176
	v_mul_f32_e32 v13, v13, v176
	v_cvt_pk_bf16_f32 v10, v10, v11
	v_cvt_pk_bf16_f32 v11, v12, v13
	global_store_dwordx2 v[178:179], v[10:11], off offset:96
	v_mul_f32_e32 v30, v30, v176
	v_mul_f32_e32 v31, v31, v176
	v_mul_f32_e32 v32, v32, v176
	v_mul_f32_e32 v33, v33, v176
	v_cvt_pk_bf16_f32 v30, v30, v31
	v_cvt_pk_bf16_f32 v31, v32, v33
	global_store_dwordx2 v[178:179], v[30:31], off offset:48
	v_mul_f32_e32 v14, v14, v176
	v_mul_f32_e32 v15, v15, v176
	v_mul_f32_e32 v16, v16, v176
	v_mul_f32_e32 v17, v17, v176
	v_cvt_pk_bf16_f32 v14, v14, v15
	v_cvt_pk_bf16_f32 v15, v16, v17
	global_store_dwordx2 v[178:179], v[14:15], off offset:112
	s_and_saveexec_b64 s[10:11], s[40:41]
	s_cbranch_execz .LBB0_521
	v_log_f32_e32 v182, v174
	v_mul_lo_u32 v180, v172, s5
	v_mov_b32_e32 v181, 0
	v_lshl_add_u64 v[180:181], v[180:181], 2, s[8:9]
	v_add_f32_e32 v182, v145, v182
	global_store_dword v[180:181], v182, off
	s_branch .LBB0_521

; __global__ void __launch_bounds__(NTHR, 2) fwd_mega(Args args) {
	.amdhsa_kernel _Z8fwd_mega4Args
		.amdhsa_group_segment_fixed_size 0
		.amdhsa_private_segment_fixed_size 0
		.amdhsa_kernarg_size 448
		.amdhsa_user_sgpr_count 2
		.amdhsa_user_sgpr_dispatch_ptr 0
		.amdhsa_user_sgpr_queue_ptr 0
		.amdhsa_user_sgpr_kernarg_segment_ptr 1
		.amdhsa_user_sgpr_dispatch_id 0
		.amdhsa_user_sgpr_kernarg_preload_length 0
		.amdhsa_user_sgpr_kernarg_preload_offset 0
		.amdhsa_user_sgpr_private_segment_size 0
		.amdhsa_uses_dynamic_stack 0
		.amdhsa_enable_private_segment 0
		.amdhsa_system_sgpr_workgroup_id_x 1
		.amdhsa_system_sgpr_workgroup_id_y 0
		.amdhsa_system_sgpr_workgroup_id_z 0
		.amdhsa_system_sgpr_workgroup_info 0
		.amdhsa_system_vgpr_workitem_id 2
		.amdhsa_next_free_vgpr 256
		.amdhsa_next_free_sgpr 100
		.amdhsa_accum_offset 256
		.amdhsa_reserve_vcc 1
		.amdhsa_float_round_mode_32 0
		.amdhsa_float_round_mode_16_64 0
		.amdhsa_float_denorm_mode_32 3
		.amdhsa_float_denorm_mode_16_64 3
		.amdhsa_dx10_clamp 1
		.amdhsa_ieee_mode 1
		.amdhsa_fp16_overflow 0
		.amdhsa_tg_split 0
		.amdhsa_exception_fp_ieee_invalid_op 0
		.amdhsa_exception_fp_denorm_src 0
		.amdhsa_exception_fp_ieee_div_zero 0
		.amdhsa_exception_fp_ieee_overflow 0
		.amdhsa_exception_fp_ieee_underflow 0
		.amdhsa_exception_fp_ieee_inexact 0
		.amdhsa_exception_int_div_zero 0
	.end_amdhsa_kernel

; __global__ void __launch_bounds__(NTHR, 2) fwd_mega(Args args) {
amdhsa.kernels:
  - .agpr_count:     0
    .args:
      - .offset:         0
        .size:           192
        .value_kind:     by_value
      - .offset:         192
        .size:           4
        .value_kind:     hidden_block_count_x
      - .offset:         196
        .size:           4
        .value_kind:     hidden_block_count_y
      - .offset:         200
        .size:           4
        .value_kind:     hidden_block_count_z
      - .offset:         204
        .size:           2
        .value_kind:     hidden_group_size_x
      - .offset:         206
        .size:           2
        .value_kind:     hidden_group_size_y
      - .offset:         208
        .size:           2
        .value_kind:     hidden_group_size_z
      - .offset:         210
        .size:           2
        .value_kind:     hidden_remainder_x
      - .offset:         212
        .size:           2
        .value_kind:     hidden_remainder_y
      - .offset:         214
        .size:           2
        .value_kind:     hidden_remainder_z
      - .offset:         232
        .size:           8
        .value_kind:     hidden_global_offset_x
      - .offset:         240
        .size:           8
        .value_kind:     hidden_global_offset_y
      - .offset:         248
        .size:           8
        .value_kind:     hidden_global_offset_z
      - .offset:         256
        .size:           2
        .value_kind:     hidden_grid_dims
      - .offset:         280
        .size:           8
        .value_kind:     hidden_multigrid_sync_arg
      - .offset:         312
        .size:           4
        .value_kind:     hidden_dynamic_lds_size
    .group_segment_fixed_size: 0
    .kernarg_segment_align: 8
    .kernarg_segment_size: 448
    .language:       OpenCL C
    .language_version:
      - 2
      - 0
    .max_flat_workgroup_size: 512
    .name:           _Z8fwd_mega4Args
    .private_segment_fixed_size: 0
    .sgpr_count:     106
    .sgpr_spill_count: 158
    .symbol:         _Z8fwd_mega4Args.kd
    .uniform_work_group_size: 1
    .uses_dynamic_stack: false
    .vgpr_count:     256
    .vgpr_spill_count: 0
    .wavefront_size: 64
